# guard: seam 9 leader waits for the previous (split-phase) generation to complete before its cross-XCD arrive
# baseline (speedup 1.0000x reference)
.LBB0_1000:
	s_andn2_saveexec_b64 s[6:7], s[6:7]
	s_cbranch_execz .LBB0_1018
	s_mov_b64 s[6:7], exec
	v_readlane_b32 s84, v255, 0
	s_cmp_lg_u32 s84, 0
	s_cbranch_scc1 .Lg9
	s_add_u32 s86, s78, 0x1e03500
	s_addc_u32 s87, s79, 0
	v_mov_b32_e32 v3, 0
.Lw9:
	global_load_dword v4, v3, s[86:87] sc1
	s_waitcnt vmcnt(0)
	v_readfirstlane_b32 s84, v4
	s_cmp_ge_u32 s84, 5
	s_cbranch_scc1 .Lg9
	s_sleep 1
	s_branch .Lw9
.Lg9:
	buffer_wbl2 sc1
	s_waitcnt lgkmcnt(0)
	s_waitcnt vmcnt(0)
	v_mbcnt_lo_u32_b32 v1, s6, 0
	v_mbcnt_hi_u32_b32 v1, s7, v1
	v_cmp_eq_u32_e32 vcc, 0, v1
	s_and_saveexec_b64 s[8:9], vcc
	s_cbranch_execz .LBB0_1003
	s_bcnt1_i32_b64 s6, s[6:7]
	v_mov_b32_e32 v2, 0x1e03000
	v_mov_b32_e32 v3, s6
	global_atomic_add v2, v2, v3, s[78:79] offset:1024 sc0
